# nt hint on the 8-bit merge-gate stores of the gates GEMM epilogue (written once, read once by the merge GEMM)
# baseline (speedup 1.0000x reference)
.LBB0_3505:
	s_mul_i32 s12, s58, 48
	s_add_i32 s44, s12, s15
	s_ashr_i32 s45, s44, 31
	v_cndmask_b32_e64 v4, 0, 1, s[10:11]
	v_lshl_add_u32 v148, v165, 4, v167
	v_cmp_ne_u32_e64 s[12:13], 1, v4
	s_andn2_b64 vcc, exec, s[10:11]
	s_lshl_b64 s[44:45], s[44:45], 16
	s_cbranch_vccnz .LBB0_3507
	s_add_u32 s10, s1, s44
	v_add_u32_e32 v4, s87, v148
	s_addc_u32 s11, s70, s45
	v_ashrrev_i32_e32 v5, 31, v4
	v_lshl_add_u64 v[4:5], v[4:5], 4, s[10:11]
	global_store_dwordx4 v[4:5], v[142:145], off nt

.LBB0_3527:
	s_add_u32 s48, s1, s44
	v_add_u32_e32 v4, s90, v148
	s_addc_u32 s49, s70, s45
	v_ashrrev_i32_e32 v5, 31, v4
	v_lshl_add_u64 v[4:5], v[4:5], 4, s[48:49]
	global_store_dwordx4 v[4:5], v[126:129], off nt
	s_and_b64 vcc, exec, s[6:7]
	s_cbranch_vccnz .LBB0_3536
	s_branch .LBB0_3533

.LBB0_3552:
	s_add_u32 s48, s1, s44
	v_add_u32_e32 v4, s92, v148
	s_addc_u32 s49, s70, s45
	v_ashrrev_i32_e32 v5, 31, v4
	v_lshl_add_u64 v[4:5], v[4:5], 4, s[48:49]
	global_store_dwordx4 v[4:5], v[110:113], off nt
	s_and_b64 vcc, exec, s[6:7]
	s_cbranch_vccnz .LBB0_3561
	s_branch .LBB0_3558

.LBB0_3577:
	s_add_u32 s48, s1, s44
	v_add_u32_e32 v4, s93, v148
	s_addc_u32 s49, s70, s45
	v_ashrrev_i32_e32 v5, 31, v4
	v_lshl_add_u64 v[4:5], v[4:5], 4, s[48:49]
	global_store_dwordx4 v[4:5], v[94:97], off nt
	s_and_b64 vcc, exec, s[6:7]
	s_cbranch_vccnz .LBB0_3586
	s_branch .LBB0_3583

.LBB0_3602:
	s_add_u32 s48, s1, s44
	v_add_u32_e32 v4, s96, v148
	s_addc_u32 s49, s70, s45
	v_ashrrev_i32_e32 v5, 31, v4
	v_lshl_add_u64 v[4:5], v[4:5], 4, s[48:49]
	global_store_dwordx4 v[4:5], v[78:81], off nt
	s_and_b64 vcc, exec, s[6:7]
	s_cbranch_vccnz .LBB0_3611
	s_branch .LBB0_3608

.LBB0_3627:
	s_add_u32 s48, s1, s44
	v_add_u32_e32 v4, s40, v148
	s_addc_u32 s49, s70, s45
	v_ashrrev_i32_e32 v5, 31, v4
	v_lshl_add_u64 v[4:5], v[4:5], 4, s[48:49]
	global_store_dwordx4 v[4:5], v[62:65], off nt
	s_and_b64 vcc, exec, s[6:7]
	s_cbranch_vccnz .LBB0_3636
	s_branch .LBB0_3633

.LBB0_3652:
	s_add_u32 s48, s1, s44
	v_add_u32_e32 v4, s46, v148
	s_addc_u32 s49, s70, s45
	v_ashrrev_i32_e32 v5, 31, v4
	v_lshl_add_u64 v[4:5], v[4:5], 4, s[48:49]
	global_store_dwordx4 v[4:5], v[38:41], off nt
	s_and_b64 vcc, exec, s[6:7]
	s_cbranch_vccnz .LBB0_3661
	s_branch .LBB0_3658

.LBB0_3677:
	s_add_u32 s8, s1, s44
	v_add_u32_e32 v4, s47, v148
	s_addc_u32 s9, s70, s45
	v_ashrrev_i32_e32 v5, 31, v4
	v_lshl_add_u64 v[4:5], v[4:5], 4, s[8:9]
	global_store_dwordx4 v[4:5], v[14:17], off nt
	s_and_b64 vcc, exec, s[6:7]
	s_cbranch_vccz .LBB0_3684
